# taps job (P0b): the 16 LDS reads of each 64-term dot product issued together into 64 registers instead of one reused quad with lgkmcnt(0) after every read; same fma / mul+add order
# speedup vs baseline: 1.0120x; 1.0120x over previous
; __device__ __forceinline__ void taps_job(const Params& p, char* smem, int l, int Lsel, int tch, int cc) {
;     ...
;   for (int tt = 0; tt < 64; ++tt) {
;     int t = tch * 64 + tt;
;     float a = 0.f;
; #pragma unroll
;     for (int j = 0; j < 64; ++j) a += hs[tt * 64 + j] * w3r[j];
;     float tl = (float)t / (float)(L - 1);
;     float val = a * expf(-tl * delta);
;     if (!(dir == 1 && t == 0)) ssp += val * val;
;     ot[c * 66 + tt] = f2bf(val);
;   }
;   atomicAdd((float*)(ws + OFF_FSS) + ((l * 2 + Lsel) * 2 + o) * 256 + c, ssp);
;   __syncthreads();
.LBB0_163:
	v_mov_b32_e32 v92, s57
	ds_read_b128 v[186:189], v92
	ds_read_b128 v[190:193], v92 offset:16
	ds_read_b128 v[194:197], v92 offset:32
	ds_read_b128 v[198:201], v92 offset:48
	ds_read_b128 v[202:205], v92 offset:64
	ds_read_b128 v[206:209], v92 offset:80
	ds_read_b128 v[210:213], v92 offset:96
	ds_read_b128 v[214:217], v92 offset:112
	ds_read_b128 v[218:221], v92 offset:128
	ds_read_b128 v[222:225], v92 offset:144
	ds_read_b128 v[226:229], v92 offset:160
	ds_read_b128 v[230:233], v92 offset:176
	ds_read_b128 v[240:243], v92 offset:192
	ds_read_b128 v[244:247], v92 offset:208
	ds_read_b128 v[248:251], v92 offset:224
	ds_read_b128 v[252:255], v92 offset:240
	s_cmp_eq_u32 s63, 0
	s_waitcnt vmcnt(0)
	s_waitcnt lgkmcnt(12)
	v_fma_f32 v93, v12, v186, 0
	v_fmac_f32_e32 v93, v13, v187
	v_fmac_f32_e32 v93, v14, v188
	v_fmac_f32_e32 v93, v15, v189
	v_fmac_f32_e32 v93, v16, v190
	v_fmac_f32_e32 v93, v17, v191
	v_fmac_f32_e32 v93, v18, v192
	v_fmac_f32_e32 v93, v19, v193
	v_fmac_f32_e32 v93, v20, v194
	v_fmac_f32_e32 v93, v21, v195
	v_fmac_f32_e32 v93, v22, v196
	v_fmac_f32_e32 v93, v23, v197
	v_fmac_f32_e32 v93, v24, v198
	v_fmac_f32_e32 v93, v25, v199
	v_fmac_f32_e32 v93, v26, v200
	v_fmac_f32_e32 v93, v27, v201
	s_waitcnt lgkmcnt(8)
	v_fmac_f32_e32 v93, v28, v202
	v_fmac_f32_e32 v93, v29, v203
	v_fmac_f32_e32 v93, v30, v204
	v_fmac_f32_e32 v93, v31, v205
	v_fmac_f32_e32 v93, v32, v206
	v_fmac_f32_e32 v93, v33, v207
	v_fmac_f32_e32 v93, v34, v208
	v_fmac_f32_e32 v93, v35, v209
	v_fmac_f32_e32 v93, v36, v210
	v_fmac_f32_e32 v93, v37, v211
	v_fmac_f32_e32 v93, v38, v212
	v_fmac_f32_e32 v93, v39, v213
	v_fmac_f32_e32 v93, v40, v214
	v_fmac_f32_e32 v93, v41, v215
	v_fmac_f32_e32 v93, v42, v216
	v_fmac_f32_e32 v93, v43, v217
	s_waitcnt lgkmcnt(4)
	v_fmac_f32_e32 v93, v44, v218
	v_fmac_f32_e32 v93, v45, v219
	v_fmac_f32_e32 v93, v46, v220
	v_fmac_f32_e32 v93, v47, v221
	v_fmac_f32_e32 v93, v48, v222
	v_fmac_f32_e32 v93, v49, v223
	v_fmac_f32_e32 v93, v50, v224
	v_fmac_f32_e32 v93, v51, v225
	v_fmac_f32_e32 v93, v52, v226
	v_fmac_f32_e32 v93, v53, v227
	v_fmac_f32_e32 v93, v54, v228
	v_fmac_f32_e32 v93, v55, v229
	v_fmac_f32_e32 v93, v56, v230
	v_fmac_f32_e32 v93, v57, v231
	v_fmac_f32_e32 v93, v58, v232
	v_fmac_f32_e32 v93, v59, v233
	s_waitcnt lgkmcnt(0)
	v_fmac_f32_e32 v93, v60, v240
	v_fmac_f32_e32 v93, v61, v241
	v_fmac_f32_e32 v93, v62, v242
	v_fmac_f32_e32 v93, v63, v243
	v_fmac_f32_e32 v93, v64, v244
	v_fmac_f32_e32 v93, v66, v245
	v_fmac_f32_e32 v93, v68, v246
	v_fmac_f32_e32 v93, v69, v247
	v_pk_mul_f32 v[76:77], v[2:3], v[248:249]
	s_nop 0
	v_add_f32_e32 v76, v93, v76
	v_add_f32_e32 v80, v76, v77
	v_pk_mul_f32 v[76:77], v[4:5], v[250:251]
	s_nop 0
	v_add_f32_e32 v76, v80, v76
	v_add_f32_e32 v80, v76, v77
	v_pk_mul_f32 v[76:77], v[6:7], v[252:253]
	s_nop 0
	v_add_f32_e32 v76, v80, v76
	v_add_f32_e32 v80, v76, v77
	v_pk_mul_f32 v[76:77], v[8:9], v[254:255]
	s_nop 0
	v_add_f32_e32 v76, v80, v76
	v_add_f32_e32 v76, v76, v77
	v_cvt_f32_u32_e32 v77, s63
	v_div_scale_f32 v78, s[10:11], v74, v74, -v77
	v_rcp_f32_e32 v79, v78
	s_mov_b32 s10, 0x3fb8aa3b
	v_fma_f32 v80, -v78, v79, 1.0
	v_fmac_f32_e32 v79, v80, v79
	v_div_scale_f32 v80, vcc, -v77, v74, -v77
	v_mul_f32_e32 v81, v80, v79
	v_fma_f32 v82, -v78, v81, v80
	v_fmac_f32_e32 v81, v82, v79
	v_fma_f32 v78, -v78, v81, v80
	v_div_fmas_f32 v78, v78, v79, v81
	v_div_fixup_f32 v77, v78, v74, -v77
	v_mul_f32_e64 v77, |v11|, v77
	v_mul_f32_e32 v78, 0x3fb8aa3b, v77
	v_fma_f32 v79, v77, s10, -v78
	v_rndne_f32_e32 v80, v78
	v_fmac_f32_e32 v79, 0x32a5705f, v77
	v_sub_f32_e32 v78, v78, v80
	v_add_f32_e32 v78, v78, v79
	v_exp_f32_e32 v78, v78
	v_cvt_i32_f32_e32 v79, v80
	s_mov_b32 s10, 0xc2ce8ed0
	v_cmp_ngt_f32_e32 vcc, s10, v77
	s_mov_b32 s10, 0x42b17218
	v_ldexp_f32 v78, v78, v79
	v_cndmask_b32_e32 v78, 0, v78, vcc
	v_cmp_nlt_f32_e32 vcc, s10, v77
	s_cselect_b64 s[10:11], -1, 0
	s_add_i32 s63, s63, 1
	v_cndmask_b32_e32 v77, v72, v78, vcc
	v_mul_f32_e32 v76, v77, v76
	s_and_b64 vcc, s[54:55], s[10:11]
	v_fma_f32 v77, v76, v76, v10
	v_cndmask_b32_e32 v10, v77, v10, vcc
	v_bfe_u32 v77, v76, 16, 1
	v_add3_u32 v76, v76, v77, s87
	v_add_u32_e32 v77, s91, v75
	s_add_i32 s91, s91, 2
	s_addk_i32 s57, 0x100
	s_cmpk_eq_i32 s91, 0x80
	ds_write_b16_d16_hi v77, v76
	s_cbranch_scc0 .LBB0_163
	s_lshr_b32 s33, s56, 1
	s_lshl_b32 s40, s0, 2
	s_and_b64 s[10:11], s[4:5], exec
	s_cselect_b32 s10, 0, 2
	s_or_b32 s10, s40, s10
	s_or_b32 s10, s10, s33
	s_lshl_b32 s10, s10, 8
	s_ashr_i32 s11, s10, 31
	s_lshl_b64 s[10:11], s[10:11], 2
	s_add_u32 s10, s52, s10
	s_addc_u32 s11, s53, s11
	v_lshl_add_u64 v[2:3], v[0:1], 2, s[10:11]
	v_add_co_u32_e32 v2, vcc, 0x1b2c8000, v2
	v_and_b32_e32 v4, 63, v0
	s_nop 0
	v_addc_co_u32_e32 v3, vcc, 0, v3, vcc
	global_atomic_add_f32 v[2:3], v10, off
	v_or_b32_e32 v1, s61, v4
	v_cmp_ne_u32_e32 vcc, 0, v1
	s_xor_b64 s[10:11], s[54:55], -1
	s_or_b64 s[10:11], s[10:11], vcc
	s_waitcnt lgkmcnt(0)
	s_barrier
	s_and_saveexec_b64 s[54:55], s[10:11]
	s_cbranch_execz .LBB0_168
	v_ashrrev_i32_e32 v5, 6, v0
	v_cmp_gt_i32_e32 vcc, s82, v5
	s_and_b64 exec, exec, vcc
	s_cbranch_execz .LBB0_168
	s_add_u32 s10, s52, 0x1b248000
	s_addc_u32 s11, s53, 0
	s_lshl_b64 s[0:1], s[0:1], 24
	s_add_u32 s0, s52, s0
	s_addc_u32 s1, s53, s1
	s_add_u32 s33, s0, 0x19248000
	s_addc_u32 s40, s1, 0
	s_and_b64 s[0:1], s[4:5], exec
	s_cselect_b32 s0, s40, s11
	s_cselect_b32 s1, s33, s10
	s_cmp_eq_u32 s62, 0
	v_sub_u32_e32 v0, 0, v1
	s_cselect_b64 vcc, -1, 0
	v_cndmask_b32_e32 v0, v0, v1, vcc
	v_mov_b32_e32 v3, s0
	v_add_u32_e32 v0, s48, v0
	s_lshl_b32 s0, s59, 7
	v_mov_b32_e32 v2, s1
	s_and_b32 s10, s0, 0x100
	v_ashrrev_i32_e32 v1, 31, v0
	s_and_b64 s[0:1], s[4:5], exec
	v_lshl_add_u64 v[0:1], v[0:1], 1, v[2:3]
	v_add_u32_e32 v6, -4, v5
	v_add_u32_e32 v2, s10, v5
	v_mul_lo_u32 v5, v5, s86
	v_lshlrev_b32_e32 v4, 1, v4
	s_cselect_b32 s4, 14, 9
	v_ashrrev_i32_e32 v3, 31, v2
	v_add3_u32 v4, v5, v4, s84
	s_mov_b64 s[0:1], 0
